# ret_states: B-operand LDS reads double-buffered (v[92:95]/v[96:99]) and issued two MFMAs ahead with counted lgkmcnt waits; on top of v38
# speedup vs baseline: 1.0072x; 1.0072x over previous
; #define LAS __attribute__((address_space(3)))
; #define LDS_WAIT() asm volatile("s_waitcnt lgkmcnt(0)" ::: "memory")
; #define MFMA16(a, b, c) __builtin_amdgcn_mfma_f32_16x16x32_bf16((a), (b), (c), 0, 0, 0)
; __device__ __forceinline__ void ret_states_phase(LAS unsigned char* lds, int wave, int lane_) {
;     ...
; #pragma unroll
;             for (int ks = 0; ks < 4; ++ks) {
;                 const bf16x8 av = *(const LAS bf16x8*)(Vt + (16 * wave + fr) * KP + 32 * ks + 8 * fq);
; #pragma unroll
;                 for (int nb = 0; nb < 4; ++nb) { const bf16x8 bk = *(const LAS bf16x8*)(Kt + (nb * 16 + fr) * KP + 32 * ks + 8 * fq); acc[nb] = MFMA16(av, bk, acc[nb]); }
;             }
;             LDS_WAIT(); __syncthreads();
.LBB0_575:
	ds_read_b128 v[88:91], v66 offset:17408
	ds_read_b128 v[92:95], v85
	ds_read_b128 v[96:99], v86
	v_mov_b32_e32 v81, v80
	v_pk_mul_f32 v[50:51], v[80:81], v[50:51]
	v_pk_mul_f32 v[48:49], v[82:83], v[48:49]
	v_pk_mul_f32 v[54:55], v[80:81], v[54:55]
	v_pk_mul_f32 v[52:53], v[82:83], v[52:53]
	v_pk_mul_f32 v[58:59], v[80:81], v[58:59]
	v_pk_mul_f32 v[56:57], v[82:83], v[56:57]
	v_pk_mul_f32 v[46:47], v[80:81], v[46:47]
	v_pk_mul_f32 v[44:45], v[82:83], v[44:45]
	s_add_i32 s29, s29, -1
	s_add_i32 s27, s27, 1
	s_waitcnt lgkmcnt(1)
	v_mfma_f32_16x16x32_bf16 v[48:51], v[88:91], v[92:95], v[48:51]
	ds_read_b128 v[92:95], v86 offset:4352
	s_waitcnt lgkmcnt(1)
	v_mfma_f32_16x16x32_bf16 v[52:55], v[88:91], v[96:99], v[52:55]
	ds_read_b128 v[96:99], v86 offset:8704
	s_waitcnt lgkmcnt(1)
	v_mfma_f32_16x16x32_bf16 v[56:59], v[88:91], v[92:95], v[56:59]
	ds_read_b128 v[92:95], v85 offset:64
	s_waitcnt lgkmcnt(1)
	v_mfma_f32_16x16x32_bf16 v[44:47], v[88:91], v[96:99], v[44:47]
	ds_read_b128 v[88:91], v66 offset:17472
	ds_read_b128 v[96:99], v86 offset:64
	s_waitcnt lgkmcnt(1)
	v_mfma_f32_16x16x32_bf16 v[48:51], v[88:91], v[92:95], v[48:51]
	ds_read_b128 v[92:95], v86 offset:4416
	s_waitcnt lgkmcnt(1)
	v_mfma_f32_16x16x32_bf16 v[52:55], v[88:91], v[96:99], v[52:55]
	ds_read_b128 v[96:99], v86 offset:8768
	s_waitcnt lgkmcnt(1)
	v_mfma_f32_16x16x32_bf16 v[56:59], v[88:91], v[92:95], v[56:59]
	ds_read_b128 v[92:95], v85 offset:128
	s_waitcnt lgkmcnt(1)
	v_mfma_f32_16x16x32_bf16 v[44:47], v[88:91], v[96:99], v[44:47]
	ds_read_b128 v[88:91], v66 offset:17536
	ds_read_b128 v[96:99], v86 offset:128
	s_waitcnt lgkmcnt(1)
	v_mfma_f32_16x16x32_bf16 v[48:51], v[88:91], v[92:95], v[48:51]
	ds_read_b128 v[92:95], v86 offset:4480
	s_waitcnt lgkmcnt(1)
	v_mfma_f32_16x16x32_bf16 v[52:55], v[88:91], v[96:99], v[52:55]
	ds_read_b128 v[96:99], v86 offset:8832
	s_waitcnt lgkmcnt(1)
	v_mfma_f32_16x16x32_bf16 v[56:59], v[88:91], v[92:95], v[56:59]
	ds_read_b128 v[92:95], v85 offset:192
	s_waitcnt lgkmcnt(1)
	v_mfma_f32_16x16x32_bf16 v[44:47], v[88:91], v[96:99], v[44:47]
	ds_read_b128 v[88:91], v66 offset:17600
	ds_read_b128 v[96:99], v86 offset:192
	s_waitcnt lgkmcnt(1)
	v_mfma_f32_16x16x32_bf16 v[48:51], v[88:91], v[92:95], v[48:51]
	ds_read_b128 v[92:95], v86 offset:4544
	s_waitcnt lgkmcnt(1)
	v_mfma_f32_16x16x32_bf16 v[52:55], v[88:91], v[96:99], v[52:55]
	ds_read_b128 v[96:99], v86 offset:8896
	s_waitcnt lgkmcnt(1)
	v_mfma_f32_16x16x32_bf16 v[56:59], v[88:91], v[92:95], v[56:59]
	s_waitcnt lgkmcnt(0)
	s_cmp_eq_u32 s29, -2
	v_mfma_f32_16x16x32_bf16 v[44:47], v[88:91], v[96:99], v[44:47]
	s_barrier
	s_cbranch_scc1 .LBB0_573
